# merged masked prev-row loads in prep2 loop 1; batched the 16 per-XCD counter loads of the first grid barrier sweep
# speedup vs baseline: 1.0160x; 1.0084x over previous
; DEVI f32x4 ld_bf4(const bf16_t* p) { u32x2 u = *(const u32x2*)p; return (f32x4){bf_lo(u.x), bf_hi(u.x), bf_lo(u.y), bf_hi(u.y)}; }
; __device__ void phase_prep2(const Params& P, int l, unsigned char* lds) {
;     ...
;     for (int i = 0; i < 4; ++i) {
;       const int c = i * 256 + lane * 4; const size_t o = (size_t)t * 1024 + c;
;       f32x4 rc = ld_bf4(pc + c), kc = ld_bf4(pc + 1024 + c), vc = ld_bf4(pc + 2048 + c);
;       f32x4 rp = hp ? ld_bf4(pp + c) : z4, kp = hp ? ld_bf4(pp + 1024 + c) : z4, vp = hp ? ld_bf4(pp + 2048 + c) : z4;
.LBB0_109:
	v_readlane_b32 s2, v251, 30
	v_readlane_b32 s3, v251, 31
	v_lshlrev_b32_e32 v0, 1, v38
	v_cmp_lt_i32_e64 s[40:41], 0, v40
	v_mov_b64_e32 v[2:3], s[2:3]
	s_movk_i32 s2, 0x3600
	v_mad_i64_i32 v[2:3], s[2:3], v40, s2, v[2:3]
	s_mov_b64 s[2:3], 0x1000
	s_nop 0
	v_lshl_add_u64 v[84:85], v[2:3], 0, s[2:3]
	v_lshl_add_u64 v[86:87], v[2:3], 0, v[0:1]
	v_lshl_add_u64 v[4:5], v[84:85], 0, v[0:1]
	global_load_dwordx2 v[16:17], v[86:87], off
	global_load_dwordx2 v[14:15], v[86:87], off offset:2048
	global_load_dwordx2 v[6:7], v[4:5], off
	s_movk_i32 s2, 0xca00
	s_mov_b32 s3, -1
	v_lshl_add_u64 v[78:79], v[2:3], 0, s[2:3]
	v_mov_b32_e32 v100, 0
	v_mov_b32_e32 v101, 0
	v_mov_b32_e32 v107, 0
	v_mov_b32_e32 v106, 0
	v_mov_b32_e32 v108, 0
	s_movk_i32 s2, 0xd200
	s_mov_b32 s3, -1
	v_lshl_add_u64 v[80:81], v[2:3], 0, s[2:3]
	v_mov_b32_e32 v110, 0
	v_mov_b32_e32 v109, 0
	v_mov_b32_e32 v111, 0
	s_movk_i32 s2, 0xda00
	s_mov_b32 s3, -1
	v_lshl_add_u64 v[82:83], v[2:3], 0, s[2:3]
	v_mov_b32_e32 v8, 0
	v_mov_b32_e32 v10, 0
	v_mov_b32_e32 v9, 0
	v_mov_b32_e32 v11, 0
	s_and_saveexec_b64 s[8:9], s[40:41]
	s_cbranch_execz .LBB0_115
	v_lshl_add_u64 v[124:125], v[78:79], 0, v[0:1]
	global_load_dwordx2 v[124:125], v[124:125], off
	v_lshl_add_u64 v[126:127], v[80:81], 0, v[0:1]
	global_load_dwordx2 v[126:127], v[126:127], off
	v_lshl_add_u64 v[128:129], v[82:83], 0, v[0:1]
	global_load_dwordx2 v[128:129], v[128:129], off
	s_waitcnt vmcnt(0)
	v_lshlrev_b32_e32 v101, 16, v124
	v_and_b32_e32 v107, 0xffff0000, v124
	v_lshlrev_b32_e32 v106, 16, v125
	v_and_b32_e32 v108, 0xffff0000, v125
	v_lshlrev_b32_e32 v100, 16, v126
	v_and_b32_e32 v110, 0xffff0000, v126
	v_lshlrev_b32_e32 v109, 16, v127
	v_and_b32_e32 v111, 0xffff0000, v127
	v_lshlrev_b32_e32 v8, 16, v128
	v_and_b32_e32 v10, 0xffff0000, v128
	v_lshlrev_b32_e32 v9, 16, v129
	v_and_b32_e32 v11, 0xffff0000, v129

; DEVI float sigmoidf_(float x) { return 1.f / (1.f + __expf(-x)); }
; __device__ void phase_prep2(const Params& P, int l, unsigned char* lds) {
;     ...
;       f32x4 r = rc + (rp - rc) * *(const f32x4*)(mu + c);
;       f32x4 k = kc + (kp - kc) * *(const f32x4*)(mu + 1024 + c);
;       f32x4 v = vc + (vp - vc) * *(const f32x4*)(mu + 2048 + c);
;       if (l > 0) {
;         f32x4 vg = *(const f32x4*)(VG + o), vf = *(const f32x4*)(VF + o), vz = *(const f32x4*)(v0 + c);
; #pragma unroll
;         for (int e = 0; e < 4; ++e) v[e] = v[e] + (vf[e] - v[e]) * sigmoidf_(vz[e] + vg[e]);
;       } else { *(f32x4*)(VF + o) = v; }
;       f32x4 lw = *(const f32x4*)(LW + o), la = *(const f32x4*)(LA + o);
;       f32x4 w0v = *(const f32x4*)(w0 + c), a0v = *(const f32x4*)(a0 + c), kkv = *(const f32x4*)(k_k + c), kav = *(const f32x4*)(k_a + c);
;       f32x4 dec, al, kk, kh; float ss = 0.f;
; #pragma unroll
;       for (int e = 0; e < 4; ++e) {
;         float z = w0v[e] + lw[e];
;         float sp = fmaxf(-z, 0.f) + __logf(1.f + __expf(-fabsf(z)));
;         float wl = -sp - 0.5f;
;         dec[e] = __expf(-__expf(wl));
;         al[e] = sigmoidf_(a0v[e] + la[e]);
;         kk[e] = k[e] * kkv[e]; ss += kk[e] * kk[e];
;         kh[e] = k[e] * (1.f + (al[e] - 1.f) * kav[e]);
;       }
;       ss = sum16(ss);
;       const float inv = 1.f / fmaxf(sqrtf(ss), 1e-12f);
.LBB0_119:
	v_readlane_b32 s2, v251, 44
	v_readlane_b32 s3, v251, 45
	v_lshlrev_b32_e32 v112, 16, v16
	v_and_b32_e32 v113, 0xffff0000, v16
	v_lshl_add_u64 v[96:97], s[2:3], 0, v[90:91]
	v_readlane_b32 s2, v251, 46
	v_readlane_b32 s3, v251, 47
	v_lshlrev_b32_e32 v114, 16, v17
	v_and_b32_e32 v115, 0xffff0000, v17
	v_lshl_add_u64 v[94:95], s[2:3], 0, v[90:91]
	global_load_dwordx4 v[26:29], v[50:51], off
	global_load_dwordx4 v[18:21], v[52:53], off
	global_load_dwordx4 v[30:33], v[96:97], off
	global_load_dwordx4 v[22:25], v[94:95], off
	v_lshlrev_b32_e32 v116, 16, v14
	v_and_b32_e32 v117, 0xffff0000, v14
	v_lshlrev_b32_e32 v98, 16, v15
	v_and_b32_e32 v99, 0xffff0000, v15
	global_load_dwordx4 v[14:17], v[54:55], off
	global_load_dwordx4 v[10:13], v[56:57], off
	v_sub_f32_e32 v119, v107, v113
	v_sub_f32_e32 v107, v108, v115
	v_sub_f32_e32 v106, v106, v114
	v_sub_f32_e32 v121, v110, v117
	v_sub_f32_e32 v120, v100, v116
	s_waitcnt vmcnt(7)
	v_pk_fma_f32 v[36:37], v[106:107], v[36:37], v[114:115]
	s_waitcnt vmcnt(6)
	v_pk_fma_f32 v[106:107], v[120:121], v[2:3], v[116:117]
	s_mov_b32 s6, 0xbfb8aa3b
	v_sub_f32_e32 v118, v101, v112
	v_sub_f32_e32 v101, v111, v99
	v_pk_fma_f32 v[34:35], v[118:119], v[34:35], v[112:113]
	s_mov_b32 s7, 0x7f800000
	v_sub_f32_e32 v100, v109, v98
	v_pk_fma_f32 v[4:5], v[100:101], v[4:5], v[98:99]
	v_mov_b32_e32 v101, 0
	v_mov_b32_e32 v100, 0
	s_waitcnt vmcnt(3)
	v_add_f32_e32 v0, v30, v26
	s_waitcnt vmcnt(2)
	v_add_f32_e32 v2, v22, v18
	v_add_f32_e32 v3, v23, v19
	v_mul_f32_e32 v2, 0xbfb8aa3b, v2
	v_mul_f32_e32 v3, 0xbfb8aa3b, v3
	v_exp_f32_e32 v2, v2
	v_exp_f32_e32 v3, v3
	v_add_f32_e32 v18, v31, v27
	v_max_f32_e64 v19, -v0, 0
	v_mul_f32_e64 v0, |v0|, s6
	v_mul_f32_e64 v22, |v18|, s6
	v_exp_f32_e32 v0, v0
	v_exp_f32_e32 v22, v22
	v_pk_add_f32 v[2:3], v[2:3], 1.0 op_sel_hi:[1,0]
	v_max_f32_e64 v18, -v18, 0
	v_div_scale_f32 v23, s[2:3], v3, v3, 1.0
	v_div_scale_f32 v27, s[2:3], v2, v2, 1.0
	v_add_f32_e32 v0, 1.0, v0
	s_mov_b32 s2, 0x800000
	v_add_f32_e32 v22, 1.0, v22
	v_cmp_gt_f32_e64 s[46:47], s2, v0
	v_cmp_gt_f32_e64 s[48:49], s2, v22
	v_rcp_f32_e32 v110, v23
	v_cndmask_b32_e64 v31, 0, 32, s[46:47]
	v_cndmask_b32_e64 v41, 0, 32, s[48:49]
	v_ldexp_f32 v0, v0, v31
	v_rcp_f32_e32 v111, v27
	v_ldexp_f32 v22, v22, v41
	v_log_f32_e32 v0, v0
	v_log_f32_e32 v22, v22
	v_fma_f32 v31, -v23, v110, 1.0
	v_fma_f32 v41, -v27, v111, 1.0
	v_fmac_f32_e32 v110, v31, v110
	v_mul_f32_e32 v31, 0x3f317217, v0
	s_mov_b32 s3, 0x3f317217
	v_div_scale_f32 v26, vcc, 1.0, v3, 1.0
	v_fmac_f32_e32 v111, v41, v111
	v_mul_f32_e32 v41, 0x3f317217, v22
	v_fma_f32 v31, v0, s3, -v31
	v_div_scale_f32 v30, s[44:45], 1.0, v2, 1.0
	v_mul_f32_e32 v112, v26, v110
	v_fma_f32 v41, v22, s3, -v41
	v_fmac_f32_e32 v31, 0x3377d1cf, v0
	v_cndmask_b32_e64 v108, 0, v187, s[46:47]
	v_mul_f32_e32 v113, v30, v111
	v_fma_f32 v114, -v23, v112, v26
	v_fmac_f32_e32 v41, 0x3377d1cf, v22
	v_fmac_f32_e32 v31, 0x3f317217, v0
	v_cmp_lt_f32_e64 s[46:47], |v0|, s7
	v_fma_f32 v115, -v27, v113, v30
	v_fmac_f32_e32 v112, v114, v110
	v_fmac_f32_e32 v41, 0x3f317217, v22
	v_cndmask_b32_e64 v0, v0, v31, s[46:47]
	v_cmp_lt_f32_e64 s[46:47], |v22|, s7
	v_cndmask_b32_e64 v109, 0, v187, s[48:49]
	v_fmac_f32_e32 v113, v115, v111
	v_fma_f32 v23, -v23, v112, v26
	v_cndmask_b32_e64 v22, v22, v41, s[46:47]
	v_sub_f32_e32 v0, v0, v108
	v_fma_f32 v26, -v27, v113, v30
	v_div_fmas_f32 v23, v23, v110, v112
	v_sub_f32_e32 v22, v22, v109
	s_mov_b64 vcc, s[44:45]
	v_add_f32_e32 v0, v19, v0
	v_div_fixup_f32 v27, v23, v3, 1.0
	v_div_fmas_f32 v3, v26, v111, v113
	v_add_f32_e32 v18, v18, v22
	v_sub_f32_e32 v0, -0.5, v0
	v_div_fixup_f32 v26, v3, v2, 1.0
	v_sub_f32_e32 v2, -0.5, v18
	v_mul_f32_e32 v0, 0x3fb8aa3b, v0
	v_mul_f32_e32 v2, 0x3fb8aa3b, v2
	v_exp_f32_e32 v0, v0
	v_exp_f32_e32 v2, v2
	v_add_f32_e32 v3, -1.0, v26
	s_waitcnt vmcnt(0)
	v_fma_f32 v10, v10, v3, 1.0
	v_mul_f32_e32 v0, 0xbfb8aa3b, v0
	v_mul_f32_e32 v2, 0xbfb8aa3b, v2
	v_exp_f32_e32 v18, v0
	v_add_f32_e32 v0, v32, v28
	v_exp_f32_e32 v19, v2
	v_mul_f32_e64 v2, |v0|, s6
	v_exp_f32_e32 v22, v2
	v_mul_f32_e32 v28, v106, v10
	v_max_f32_e64 v0, -v0, 0
	v_pk_mul_f32 v[2:3], v[106:107], v[14:15]
	v_add_f32_e32 v10, 1.0, v22
	v_cmp_gt_f32_e32 vcc, s2, v10
	v_pk_mul_f32 v[14:15], v[2:3], v[2:3]
	v_pk_mul_f32 v[16:17], v[4:5], v[16:17]
	v_cndmask_b32_e64 v22, 0, 32, vcc
	v_ldexp_f32 v10, v10, v22
	v_log_f32_e32 v10, v10
	v_add_f32_e32 v22, -1.0, v27
	v_fma_f32 v11, v11, v22, 1.0
	v_add_f32_e32 v14, v14, v15
	v_mul_f32_e32 v22, 0x3f317217, v10
	v_fma_f32 v22, v10, s3, -v22
	v_fmac_f32_e32 v22, 0x3377d1cf, v10
	v_fmac_f32_e32 v22, 0x3f317217, v10
	v_cmp_lt_f32_e64 s[44:45], |v10|, s7
	v_mov_b32_e32 v41, 0
	v_mov_b32_e32 v106, 0
	v_cndmask_b32_e64 v10, v10, v22, s[44:45]
	v_cndmask_b32_e32 v22, 0, v187, vcc
	v_sub_f32_e32 v10, v10, v22
	v_add_f32_e32 v22, v33, v29
	v_add_f32_e32 v0, v0, v10
	v_mul_f32_e64 v10, |v22|, s6
	v_exp_f32_e32 v10, v10
	v_mul_f32_e32 v29, v107, v11
	v_add_f32_e32 v11, v24, v20
	v_sub_f32_e32 v0, -0.5, v0
	v_add_f32_e32 v10, 1.0, v10
	v_cmp_gt_f32_e32 vcc, s2, v10
	v_mul_f32_e32 v0, 0x3fb8aa3b, v0
	v_exp_f32_e32 v0, v0
	v_cndmask_b32_e64 v20, 0, 32, vcc
	v_ldexp_f32 v10, v10, v20
	v_log_f32_e32 v20, v10
	v_mul_f32_e32 v10, 0xbfb8aa3b, v11
	v_max_f32_e64 v11, -v22, 0
	v_exp_f32_e32 v10, v10
	v_mul_f32_e32 v22, 0x3f317217, v20
	v_fma_f32 v22, v20, s3, -v22
	v_fmac_f32_e32 v22, 0x3377d1cf, v20
	v_fmac_f32_e32 v22, 0x3f317217, v20
	v_cmp_lt_f32_e64 s[44:45], |v20|, s7
	v_mul_f32_e32 v0, 0xbfb8aa3b, v0
	s_nop 0
	v_cndmask_b32_e64 v20, v20, v22, s[44:45]
	v_cndmask_b32_e32 v22, 0, v187, vcc
	v_sub_f32_e32 v20, v20, v22
	v_add_f32_e32 v20, v11, v20
	v_add_f32_e32 v11, v25, v21
	v_mul_f32_e32 v11, 0xbfb8aa3b, v11
	v_exp_f32_e32 v11, v11
	v_sub_f32_e32 v20, -0.5, v20
	v_mul_f32_e32 v20, 0x3fb8aa3b, v20
	v_exp_f32_e32 v21, v20
	v_pk_add_f32 v[10:11], v[10:11], 1.0 op_sel_hi:[1,0]
	v_exp_f32_e32 v20, v0
	v_div_scale_f32 v24, s[2:3], v11, v11, 1.0
	v_rcp_f32_e32 v25, v24
	v_mul_f32_e32 v0, 0xbfb8aa3b, v21
	v_exp_f32_e32 v21, v0
	v_fma_f32 v0, -v24, v25, 1.0
	v_fmac_f32_e32 v25, v0, v25
	v_div_scale_f32 v0, vcc, 1.0, v11, 1.0
	v_mul_f32_e32 v30, v0, v25
	v_fma_f32 v22, -v24, v30, v0
	v_fmac_f32_e32 v30, v22, v25
	v_pk_mul_f32 v[22:23], v[16:17], v[16:17]
	v_fma_f32 v0, -v24, v30, v0
	v_add_f32_e32 v14, v22, v14
	v_add_f32_e32 v14, v23, v14
	ds_bpermute_b32 v15, v102, v14
	v_div_scale_f32 v22, s[2:3], v10, v10, 1.0
	v_rcp_f32_e32 v23, v22
	v_div_fmas_f32 v0, v0, v25, v30
	s_waitcnt lgkmcnt(0)
; DEVI f32x4 ld_bf4(const bf16_t* p) { u32x2 u = *(const u32x2*)p; return (f32x4){bf_lo(u.x), bf_hi(u.x), bf_lo(u.y), bf_hi(u.y)}; }
; DEVI void st_bf4(bf16_t* p, f32x4 v) { u32x2 u; u.x = cvt_pk_bf16(v[0], v[1]); u.y = cvt_pk_bf16(v[2], v[3]); *(u32x2*)p = u; }
; __device__ void phase_prep2(const Params& P, int l, unsigned char* lds) {
;     ...
;     for (int i = 0; i < 4; ++i) {
;       const int c = i * 256 + lane * 4; const size_t o = (size_t)t * 1024 + c;
;       f32x4 rc = ld_bf4(pc + c), kc = ld_bf4(pc + 1024 + c), vc = ld_bf4(pc + 2048 + c);
;       f32x4 rp = hp ? ld_bf4(pp + c) : z4, kp = hp ? ld_bf4(pp + 1024 + c) : z4, vp = hp ? ld_bf4(pp + 2048 + c) : z4;
;     ...
;       ss = sum16(ss);
;       const float inv = 1.f / fmaxf(sqrtf(ss), 1e-12f);
;       kk = kk * inv;
;       *(f32x4*)(LW + o) = dec; *(f32x4*)(LA + o) = -(kk * al); *(f32x4*)(VG + o) = v; *(f32x4*)(KK + o) = kk;
;       st_bf4(KH + o, kh); st_bf4(R + o, r);
;     }
	v_add_f32_e32 v14, v14, v15
	ds_bpermute_b32 v15, v103, v14
	v_div_fixup_f32 v24, v0, v11, 1.0
	v_fma_f32 v0, -v22, v23, 1.0
	v_fmac_f32_e32 v23, v0, v23
	s_mov_b32 s2, 0xf800000
	s_waitcnt lgkmcnt(0)
	v_add_f32_e32 v0, v14, v15
	ds_bpermute_b32 v11, v104, v0
	v_div_scale_f32 v14, vcc, 1.0, v10, 1.0
	v_mul_f32_e32 v15, v14, v23
	v_fma_f32 v25, -v22, v15, v14
	s_waitcnt lgkmcnt(0)
	v_add_f32_e32 v0, v0, v11
	ds_bpermute_b32 v11, v105, v0
	v_fmac_f32_e32 v15, v25, v23
	v_fma_f32 v14, -v22, v15, v14
	v_div_fmas_f32 v14, v14, v23, v15
	v_div_fixup_f32 v14, v14, v10, 1.0
	s_waitcnt lgkmcnt(0)
	v_add_f32_e32 v0, v0, v11
	v_mul_f32_e32 v10, 0x4f800000, v0
	v_cmp_gt_f32_e32 vcc, s2, v0
	v_add_f32_e32 v11, -1.0, v14
	v_fma_f32 v11, v12, v11, 1.0
	v_cndmask_b32_e32 v0, v0, v10, vcc
	v_sqrt_f32_e32 v10, v0
	v_mul_f32_e32 v15, v4, v11
	global_store_dwordx4 v[96:97], v[18:21], off
	v_add_u32_e32 v4, -1, v10
	v_fma_f32 v11, -v4, v10, v0
	v_cmp_ge_f32_e64 s[44:45], 0, v11
	v_add_u32_e32 v11, 1, v10
	s_nop 0
	v_cndmask_b32_e64 v4, v10, v4, s[44:45]
	v_fma_f32 v10, -v11, v10, v0
	v_cmp_lt_f32_e64 s[44:45], 0, v10
	s_nop 1
	v_cndmask_b32_e64 v4, v4, v11, s[44:45]
	v_mul_f32_e32 v10, 0x37800000, v4
	v_cndmask_b32_e32 v4, v4, v10, vcc
	v_cmp_class_f32_e32 vcc, v0, v182
	v_add_f32_e32 v11, -1.0, v24
	v_fma_f32 v11, v13, v11, 1.0
	v_cndmask_b32_e32 v0, v4, v0, vcc
	v_max_f32_e32 v0, 0x2b8cbccc, v0
	v_div_scale_f32 v4, s[2:3], v0, v0, 1.0
	v_rcp_f32_e32 v10, v4
	v_mul_f32_e32 v22, v5, v11
	v_xor_b32_e32 v13, 0x80000000, v24
	v_fma_f32 v5, -v4, v10, 1.0
	v_fmac_f32_e32 v10, v5, v10
	v_div_scale_f32 v5, vcc, 1.0, v0, 1.0
	v_mul_f32_e32 v11, v5, v10
	v_fma_f32 v12, -v4, v11, v5
	v_fmac_f32_e32 v11, v12, v10
	v_fma_f32 v4, -v4, v11, v5
	v_div_fmas_f32 v4, v4, v10, v11
	v_div_fixup_f32 v0, v4, v0, 1.0
	v_pk_mul_f32 v[4:5], v[16:17], v[0:1] op_sel_hi:[1,0]
	v_pk_mul_f32 v[2:3], v[2:3], v[0:1] op_sel_hi:[1,0]
	v_xor_b32_e32 v11, 0x80000000, v27
	v_xor_b32_e32 v10, 0x80000000, v26
	v_xor_b32_e32 v12, 0x80000000, v14
	v_pk_mul_f32 v[12:13], v[4:5], v[12:13]
	v_pk_mul_f32 v[10:11], v[2:3], v[10:11]
	global_store_dwordx4 v[94:95], v[10:13], off
	global_store_dwordx4 v[92:93], v[6:9], off
	v_lshlrev_b32_e32 v0, 1, v58
	s_nop 0
	v_lshl_add_u64 v[6:7], s[30:31], 0, v[90:91]
	global_store_dwordx4 v[6:7], v[2:5], off
	v_cvt_pk_bf16_f32 v6, v28, v29
	v_cvt_pk_bf16_f32 v7, v15, v22
	v_mov_b32_e32 v8, 0
	s_nop 0
	v_lshlrev_b64 v[2:3], 1, v[88:89]
	v_lshl_add_u64 v[4:5], s[26:27], 0, v[2:3]
	v_lshl_add_u64 v[2:3], s[28:29], 0, v[2:3]
	global_store_dwordx2 v[4:5], v[6:7], off
	v_cvt_pk_bf16_f32 v4, v34, v35
	v_cvt_pk_bf16_f32 v5, v36, v37
	global_store_dwordx2 v[2:3], v[4:5], off
	v_lshl_add_u64 v[2:3], v[84:85], 0, v[0:1]
	global_load_dwordx2 v[16:17], v[86:87], off offset:512
	global_load_dwordx2 v[14:15], v[86:87], off offset:2560
	global_load_dwordx2 v[6:7], v[2:3], off
	v_mov_b32_e32 v107, 0
	v_mov_b32_e32 v109, 0
	v_mov_b32_e32 v108, 0
	v_mov_b32_e32 v110, 0
	v_mov_b32_e32 v10, 0
	v_mov_b32_e32 v9, 0
	v_mov_b32_e32 v11, 0
	s_and_saveexec_b64 s[8:9], s[40:41]
	s_cbranch_execz .LBB0_125
	v_lshl_add_u64 v[124:125], v[78:79], 0, v[0:1]
	global_load_dwordx2 v[124:125], v[124:125], off
	v_lshl_add_u64 v[126:127], v[80:81], 0, v[0:1]
	global_load_dwordx2 v[126:127], v[126:127], off
	v_lshl_add_u64 v[128:129], v[82:83], 0, v[0:1]
	global_load_dwordx2 v[128:129], v[128:129], off
	s_waitcnt vmcnt(0)
	v_lshlrev_b32_e32 v41, 16, v124
	v_and_b32_e32 v101, 0xffff0000, v124
	v_lshlrev_b32_e32 v100, 16, v125
	v_and_b32_e32 v106, 0xffff0000, v125
	v_lshlrev_b32_e32 v107, 16, v126
	v_and_b32_e32 v109, 0xffff0000, v126
	v_lshlrev_b32_e32 v108, 16, v127
	v_and_b32_e32 v110, 0xffff0000, v127
	v_lshlrev_b32_e32 v8, 16, v128
	v_and_b32_e32 v10, 0xffff0000, v128
	v_lshlrev_b32_e32 v9, 16, v129
	v_and_b32_e32 v11, 0xffff0000, v129

; DEVI float sigmoidf_(float x) { return 1.f / (1.f + __expf(-x)); }
; __device__ void phase_prep2(const Params& P, int l, unsigned char* lds) {
;     ...
;       f32x4 r = rc + (rp - rc) * *(const f32x4*)(mu + c);
;       f32x4 k = kc + (kp - kc) * *(const f32x4*)(mu + 1024 + c);
;       f32x4 v = vc + (vp - vc) * *(const f32x4*)(mu + 2048 + c);
;       if (l > 0) {
;         f32x4 vg = *(const f32x4*)(VG + o), vf = *(const f32x4*)(VF + o), vz = *(const f32x4*)(v0 + c);
; #pragma unroll
;         for (int e = 0; e < 4; ++e) v[e] = v[e] + (vf[e] - v[e]) * sigmoidf_(vz[e] + vg[e]);
;       } else { *(f32x4*)(VF + o) = v; }
;       f32x4 lw = *(const f32x4*)(LW + o), la = *(const f32x4*)(LA + o);
;       f32x4 w0v = *(const f32x4*)(w0 + c), a0v = *(const f32x4*)(a0 + c), kkv = *(const f32x4*)(k_k + c), kav = *(const f32x4*)(k_a + c);
;       f32x4 dec, al, kk, kh; float ss = 0.f;
; #pragma unroll
;       for (int e = 0; e < 4; ++e) {
;         float z = w0v[e] + lw[e];
;         float sp = fmaxf(-z, 0.f) + __logf(1.f + __expf(-fabsf(z)));
;         float wl = -sp - 0.5f;
;         dec[e] = __expf(-__expf(wl));
;         al[e] = sigmoidf_(a0v[e] + la[e]);
;         kk[e] = k[e] * kkv[e]; ss += kk[e] * kk[e];
;         kh[e] = k[e] * (1.f + (al[e] - 1.f) * kav[e]);
;       }
;       ss = sum16(ss);
;       const float inv = 1.f / fmaxf(sqrtf(ss), 1e-12f);
.LBB0_129:
	v_readlane_b32 s2, v251, 44
	v_readlane_b32 s3, v251, 45
	v_lshlrev_b32_e32 v112, 16, v16
	v_and_b32_e32 v113, 0xffff0000, v16
	v_lshl_add_u64 v[96:97], s[2:3], 0, v[90:91]
	v_readlane_b32 s2, v251, 46
	v_readlane_b32 s3, v251, 47
	v_lshlrev_b32_e32 v114, 16, v17
	v_and_b32_e32 v115, 0xffff0000, v17
	v_lshl_add_u64 v[94:95], s[2:3], 0, v[90:91]
	global_load_dwordx4 v[26:29], v[50:51], off offset:1024
	global_load_dwordx4 v[18:21], v[52:53], off offset:1024
	global_load_dwordx4 v[30:33], v[96:97], off
	global_load_dwordx4 v[22:25], v[94:95], off
	v_lshlrev_b32_e32 v116, 16, v14
	v_and_b32_e32 v117, 0xffff0000, v14
	v_lshlrev_b32_e32 v98, 16, v15
	v_and_b32_e32 v99, 0xffff0000, v15
	global_load_dwordx4 v[14:17], v[54:55], off offset:1024
	global_load_dwordx4 v[10:13], v[56:57], off offset:1024
	v_sub_f32_e32 v123, v109, v117
	v_sub_f32_e32 v122, v107, v116
	v_sub_f32_e32 v121, v106, v115
	s_waitcnt vmcnt(6)
	v_pk_fma_f32 v[106:107], v[122:123], v[2:3], v[116:117]
	v_sub_f32_e32 v119, v101, v113
	v_sub_f32_e32 v118, v41, v112
	v_sub_f32_e32 v101, v110, v99
	v_sub_f32_e32 v120, v100, v114
	v_pk_fma_f32 v[34:35], v[118:119], v[34:35], v[112:113]
	v_sub_f32_e32 v100, v108, v98
	v_pk_fma_f32 v[36:37], v[120:121], v[36:37], v[114:115]
	v_pk_fma_f32 v[4:5], v[100:101], v[4:5], v[98:99]
	v_mov_b32_e32 v101, 0
	v_mov_b32_e32 v100, 0
	s_waitcnt vmcnt(3)
	v_add_f32_e32 v0, v30, v26
	s_waitcnt vmcnt(2)
	v_add_f32_e32 v2, v22, v18
	v_add_f32_e32 v3, v23, v19
	v_mul_f32_e32 v2, 0xbfb8aa3b, v2
	v_mul_f32_e32 v3, 0xbfb8aa3b, v3
	v_exp_f32_e32 v2, v2
	v_exp_f32_e32 v3, v3
	v_add_f32_e32 v18, v31, v27
	v_max_f32_e64 v19, -v0, 0
	v_mul_f32_e64 v0, |v0|, s6
	v_mul_f32_e64 v22, |v18|, s6
	v_exp_f32_e32 v0, v0
	v_exp_f32_e32 v22, v22
	v_pk_add_f32 v[2:3], v[2:3], 1.0 op_sel_hi:[1,0]
	v_max_f32_e64 v18, -v18, 0
	v_div_scale_f32 v23, s[2:3], v3, v3, 1.0
	v_div_scale_f32 v27, s[2:3], v2, v2, 1.0
	v_add_f32_e32 v0, 1.0, v0
	s_mov_b32 s2, 0x800000
	v_add_f32_e32 v22, 1.0, v22
	v_cmp_gt_f32_e64 s[46:47], s2, v0
	v_cmp_gt_f32_e64 s[48:49], s2, v22
	v_rcp_f32_e32 v110, v23
	v_cndmask_b32_e64 v31, 0, 32, s[46:47]
	v_cndmask_b32_e64 v41, 0, 32, s[48:49]
	v_ldexp_f32 v0, v0, v31
	v_rcp_f32_e32 v111, v27
	v_ldexp_f32 v22, v22, v41
	v_log_f32_e32 v0, v0
	v_log_f32_e32 v22, v22
	v_fma_f32 v31, -v23, v110, 1.0
	v_fma_f32 v41, -v27, v111, 1.0
	v_fmac_f32_e32 v110, v31, v110
	v_mul_f32_e32 v31, 0x3f317217, v0
	s_mov_b32 s3, 0x3f317217
	v_div_scale_f32 v26, vcc, 1.0, v3, 1.0
	v_fmac_f32_e32 v111, v41, v111
	v_mul_f32_e32 v41, 0x3f317217, v22
	v_fma_f32 v31, v0, s3, -v31
	v_div_scale_f32 v30, s[44:45], 1.0, v2, 1.0
	v_mul_f32_e32 v112, v26, v110
	v_fma_f32 v41, v22, s3, -v41
	v_fmac_f32_e32 v31, 0x3377d1cf, v0
	v_cndmask_b32_e64 v108, 0, v187, s[46:47]
	v_mul_f32_e32 v113, v30, v111
	v_fma_f32 v114, -v23, v112, v26
	v_fmac_f32_e32 v41, 0x3377d1cf, v22
	v_fmac_f32_e32 v31, 0x3f317217, v0
	v_cmp_lt_f32_e64 s[46:47], |v0|, s7
	v_fma_f32 v115, -v27, v113, v30
	v_fmac_f32_e32 v112, v114, v110
	v_fmac_f32_e32 v41, 0x3f317217, v22
	v_cndmask_b32_e64 v0, v0, v31, s[46:47]
	v_cmp_lt_f32_e64 s[46:47], |v22|, s7
	v_cndmask_b32_e64 v109, 0, v187, s[48:49]
	v_fmac_f32_e32 v113, v115, v111
	v_fma_f32 v23, -v23, v112, v26
	v_cndmask_b32_e64 v22, v22, v41, s[46:47]
	v_sub_f32_e32 v0, v0, v108
	v_fma_f32 v26, -v27, v113, v30
	v_div_fmas_f32 v23, v23, v110, v112
	v_sub_f32_e32 v22, v22, v109
	s_mov_b64 vcc, s[44:45]
	v_add_f32_e32 v0, v19, v0
	v_div_fixup_f32 v27, v23, v3, 1.0
	v_div_fmas_f32 v3, v26, v111, v113
	v_add_f32_e32 v18, v18, v22
	v_sub_f32_e32 v0, -0.5, v0
	v_div_fixup_f32 v26, v3, v2, 1.0
	v_sub_f32_e32 v2, -0.5, v18
	v_mul_f32_e32 v0, 0x3fb8aa3b, v0
	v_mul_f32_e32 v2, 0x3fb8aa3b, v2
	v_exp_f32_e32 v0, v0
	v_exp_f32_e32 v2, v2
	v_add_f32_e32 v3, -1.0, v26
	s_waitcnt vmcnt(0)
	v_fma_f32 v10, v10, v3, 1.0
	v_mul_f32_e32 v0, 0xbfb8aa3b, v0
	v_mul_f32_e32 v2, 0xbfb8aa3b, v2
	v_exp_f32_e32 v18, v0
	v_add_f32_e32 v0, v32, v28
	v_exp_f32_e32 v19, v2
	v_mul_f32_e64 v2, |v0|, s6
	v_exp_f32_e32 v22, v2
	v_mul_f32_e32 v28, v106, v10
	v_max_f32_e64 v0, -v0, 0
	v_pk_mul_f32 v[2:3], v[106:107], v[14:15]
	v_add_f32_e32 v10, 1.0, v22
	v_cmp_gt_f32_e32 vcc, s2, v10
	v_pk_mul_f32 v[14:15], v[2:3], v[2:3]
	v_pk_mul_f32 v[16:17], v[4:5], v[16:17]
	v_cndmask_b32_e64 v22, 0, 32, vcc
	v_ldexp_f32 v10, v10, v22
	v_log_f32_e32 v10, v10
	v_add_f32_e32 v22, -1.0, v27
	v_fma_f32 v11, v11, v22, 1.0
	v_add_f32_e32 v14, v14, v15
	v_mul_f32_e32 v22, 0x3f317217, v10
	v_fma_f32 v22, v10, s3, -v22
	v_fmac_f32_e32 v22, 0x3377d1cf, v10
	v_fmac_f32_e32 v22, 0x3f317217, v10
	v_cmp_lt_f32_e64 s[44:45], |v10|, s7
	v_mov_b32_e32 v41, 0
	v_mov_b32_e32 v106, 0
	v_cndmask_b32_e64 v10, v10, v22, s[44:45]
	v_cndmask_b32_e32 v22, 0, v187, vcc
	v_sub_f32_e32 v10, v10, v22
	v_add_f32_e32 v22, v33, v29
	v_add_f32_e32 v0, v0, v10
	v_mul_f32_e64 v10, |v22|, s6
	v_exp_f32_e32 v10, v10
	v_mul_f32_e32 v29, v107, v11
	v_add_f32_e32 v11, v24, v20
	v_sub_f32_e32 v0, -0.5, v0
	v_add_f32_e32 v10, 1.0, v10
	v_cmp_gt_f32_e32 vcc, s2, v10
	v_mul_f32_e32 v0, 0x3fb8aa3b, v0
	v_exp_f32_e32 v0, v0
	v_cndmask_b32_e64 v20, 0, 32, vcc
	v_ldexp_f32 v10, v10, v20
	v_log_f32_e32 v20, v10
	v_mul_f32_e32 v10, 0xbfb8aa3b, v11
	v_max_f32_e64 v11, -v22, 0
	v_exp_f32_e32 v10, v10
	v_mul_f32_e32 v22, 0x3f317217, v20
	v_fma_f32 v22, v20, s3, -v22
	v_fmac_f32_e32 v22, 0x3377d1cf, v20
	v_fmac_f32_e32 v22, 0x3f317217, v20
	v_cmp_lt_f32_e64 s[44:45], |v20|, s7
	v_mul_f32_e32 v0, 0xbfb8aa3b, v0
	s_nop 0
	v_cndmask_b32_e64 v20, v20, v22, s[44:45]
	v_cndmask_b32_e32 v22, 0, v187, vcc
	v_sub_f32_e32 v20, v20, v22
	v_add_f32_e32 v20, v11, v20
	v_add_f32_e32 v11, v25, v21
	v_mul_f32_e32 v11, 0xbfb8aa3b, v11
	v_exp_f32_e32 v11, v11
	v_sub_f32_e32 v20, -0.5, v20
	v_mul_f32_e32 v20, 0x3fb8aa3b, v20
	v_exp_f32_e32 v21, v20
	v_pk_add_f32 v[10:11], v[10:11], 1.0 op_sel_hi:[1,0]
	v_exp_f32_e32 v20, v0
	v_div_scale_f32 v24, s[2:3], v11, v11, 1.0
	v_rcp_f32_e32 v25, v24
	v_mul_f32_e32 v0, 0xbfb8aa3b, v21
	v_exp_f32_e32 v21, v0
	v_fma_f32 v0, -v24, v25, 1.0
	v_fmac_f32_e32 v25, v0, v25
	v_div_scale_f32 v0, vcc, 1.0, v11, 1.0
	v_mul_f32_e32 v30, v0, v25
	v_fma_f32 v22, -v24, v30, v0
	v_fmac_f32_e32 v30, v22, v25
	v_pk_mul_f32 v[22:23], v[16:17], v[16:17]
	v_fma_f32 v0, -v24, v30, v0
	v_add_f32_e32 v14, v22, v14
	v_add_f32_e32 v14, v23, v14
	ds_bpermute_b32 v15, v102, v14
	v_div_scale_f32 v22, s[2:3], v10, v10, 1.0
	v_rcp_f32_e32 v23, v22
	v_div_fmas_f32 v0, v0, v25, v30
	s_waitcnt lgkmcnt(0)
; DEVI f32x4 ld_bf4(const bf16_t* p) { u32x2 u = *(const u32x2*)p; return (f32x4){bf_lo(u.x), bf_hi(u.x), bf_lo(u.y), bf_hi(u.y)}; }
; DEVI void st_bf4(bf16_t* p, f32x4 v) { u32x2 u; u.x = cvt_pk_bf16(v[0], v[1]); u.y = cvt_pk_bf16(v[2], v[3]); *(u32x2*)p = u; }
; __device__ void phase_prep2(const Params& P, int l, unsigned char* lds) {
;     ...
;     for (int i = 0; i < 4; ++i) {
;       const int c = i * 256 + lane * 4; const size_t o = (size_t)t * 1024 + c;
;       f32x4 rc = ld_bf4(pc + c), kc = ld_bf4(pc + 1024 + c), vc = ld_bf4(pc + 2048 + c);
;       f32x4 rp = hp ? ld_bf4(pp + c) : z4, kp = hp ? ld_bf4(pp + 1024 + c) : z4, vp = hp ? ld_bf4(pp + 2048 + c) : z4;
;     ...
;       ss = sum16(ss);
;       const float inv = 1.f / fmaxf(sqrtf(ss), 1e-12f);
;       kk = kk * inv;
;       *(f32x4*)(LW + o) = dec; *(f32x4*)(LA + o) = -(kk * al); *(f32x4*)(VG + o) = v; *(f32x4*)(KK + o) = kk;
;       st_bf4(KH + o, kh); st_bf4(R + o, r);
;     }
	v_add_f32_e32 v14, v14, v15
	ds_bpermute_b32 v15, v103, v14
	v_div_fixup_f32 v24, v0, v11, 1.0
	v_fma_f32 v0, -v22, v23, 1.0
	v_fmac_f32_e32 v23, v0, v23
	s_mov_b32 s2, 0xf800000
	s_waitcnt lgkmcnt(0)
	v_add_f32_e32 v0, v14, v15
	ds_bpermute_b32 v11, v104, v0
	v_div_scale_f32 v14, vcc, 1.0, v10, 1.0
	v_mul_f32_e32 v15, v14, v23
	v_fma_f32 v25, -v22, v15, v14
	s_waitcnt lgkmcnt(0)
	v_add_f32_e32 v0, v0, v11
	ds_bpermute_b32 v11, v105, v0
	v_fmac_f32_e32 v15, v25, v23
	v_fma_f32 v14, -v22, v15, v14
	v_div_fmas_f32 v14, v14, v23, v15
	v_div_fixup_f32 v14, v14, v10, 1.0
	s_waitcnt lgkmcnt(0)
	v_add_f32_e32 v0, v0, v11
	v_mul_f32_e32 v10, 0x4f800000, v0
	v_cmp_gt_f32_e32 vcc, s2, v0
	v_add_f32_e32 v11, -1.0, v14
	v_fma_f32 v11, v12, v11, 1.0
	v_cndmask_b32_e32 v0, v0, v10, vcc
	v_sqrt_f32_e32 v10, v0
	v_mul_f32_e32 v15, v4, v11
	global_store_dwordx4 v[96:97], v[18:21], off
	v_add_u32_e32 v4, -1, v10
	v_fma_f32 v11, -v4, v10, v0
	v_cmp_ge_f32_e64 s[44:45], 0, v11
	v_add_u32_e32 v11, 1, v10
	s_nop 0
	v_cndmask_b32_e64 v4, v10, v4, s[44:45]
	v_fma_f32 v10, -v11, v10, v0
	v_cmp_lt_f32_e64 s[44:45], 0, v10
	s_nop 1
	v_cndmask_b32_e64 v4, v4, v11, s[44:45]
	v_mul_f32_e32 v10, 0x37800000, v4
	v_cndmask_b32_e32 v4, v4, v10, vcc
	v_cmp_class_f32_e32 vcc, v0, v182
	v_add_f32_e32 v11, -1.0, v24
	v_fma_f32 v11, v13, v11, 1.0
	v_cndmask_b32_e32 v0, v4, v0, vcc
	v_max_f32_e32 v0, 0x2b8cbccc, v0
	v_div_scale_f32 v4, s[2:3], v0, v0, 1.0
	v_rcp_f32_e32 v10, v4
	v_mul_f32_e32 v22, v5, v11
	v_xor_b32_e32 v13, 0x80000000, v24
	v_fma_f32 v5, -v4, v10, 1.0
	v_fmac_f32_e32 v10, v5, v10
	v_div_scale_f32 v5, vcc, 1.0, v0, 1.0
	v_mul_f32_e32 v11, v5, v10
	v_fma_f32 v12, -v4, v11, v5
	v_fmac_f32_e32 v11, v12, v10
	v_fma_f32 v4, -v4, v11, v5
	v_div_fmas_f32 v4, v4, v10, v11
	v_div_fixup_f32 v0, v4, v0, 1.0
	v_pk_mul_f32 v[4:5], v[16:17], v[0:1] op_sel_hi:[1,0]
	v_pk_mul_f32 v[2:3], v[2:3], v[0:1] op_sel_hi:[1,0]
	v_xor_b32_e32 v11, 0x80000000, v27
	v_xor_b32_e32 v10, 0x80000000, v26
	v_xor_b32_e32 v12, 0x80000000, v14
	v_pk_mul_f32 v[12:13], v[4:5], v[12:13]
	v_pk_mul_f32 v[10:11], v[2:3], v[10:11]
	global_store_dwordx4 v[94:95], v[10:13], off
	global_store_dwordx4 v[92:93], v[6:9], off
	v_lshlrev_b32_e32 v0, 1, v64
	s_nop 0
	v_lshl_add_u64 v[6:7], s[30:31], 0, v[90:91]
	global_store_dwordx4 v[6:7], v[2:5], off
	v_cvt_pk_bf16_f32 v6, v28, v29
	v_cvt_pk_bf16_f32 v7, v15, v22
	v_mov_b32_e32 v8, 0
	s_nop 0
	v_lshlrev_b64 v[2:3], 1, v[88:89]
	v_lshl_add_u64 v[4:5], s[26:27], 0, v[2:3]
	v_lshl_add_u64 v[2:3], s[28:29], 0, v[2:3]
	global_store_dwordx2 v[4:5], v[6:7], off
	v_cvt_pk_bf16_f32 v4, v34, v35
	v_cvt_pk_bf16_f32 v5, v36, v37
	global_store_dwordx2 v[2:3], v[4:5], off
	v_lshl_add_u64 v[2:3], v[84:85], 0, v[0:1]
	global_load_dwordx2 v[16:17], v[86:87], off offset:1024
	global_load_dwordx2 v[14:15], v[86:87], off offset:3072
	global_load_dwordx2 v[6:7], v[2:3], off
	v_mov_b32_e32 v107, 0
	v_mov_b32_e32 v109, 0
	v_mov_b32_e32 v108, 0
	v_mov_b32_e32 v110, 0
	v_mov_b32_e32 v10, 0
	v_mov_b32_e32 v9, 0
	v_mov_b32_e32 v11, 0
	s_and_saveexec_b64 s[8:9], s[40:41]
	s_cbranch_execz .LBB0_135
	v_lshl_add_u64 v[124:125], v[78:79], 0, v[0:1]
	global_load_dwordx2 v[124:125], v[124:125], off
	v_lshl_add_u64 v[126:127], v[80:81], 0, v[0:1]
	global_load_dwordx2 v[126:127], v[126:127], off
	v_lshl_add_u64 v[128:129], v[82:83], 0, v[0:1]
	global_load_dwordx2 v[128:129], v[128:129], off
	s_waitcnt vmcnt(0)
	v_lshlrev_b32_e32 v41, 16, v124
	v_and_b32_e32 v101, 0xffff0000, v124
	v_lshlrev_b32_e32 v100, 16, v125
	v_and_b32_e32 v106, 0xffff0000, v125
	v_lshlrev_b32_e32 v107, 16, v126
	v_and_b32_e32 v109, 0xffff0000, v126
	v_lshlrev_b32_e32 v108, 16, v127
	v_and_b32_e32 v110, 0xffff0000, v127
	v_lshlrev_b32_e32 v8, 16, v128
	v_and_b32_e32 v10, 0xffff0000, v128
	v_lshlrev_b32_e32 v9, 16, v129
	v_and_b32_e32 v11, 0xffff0000, v129

; DEVI float sigmoidf_(float x) { return 1.f / (1.f + __expf(-x)); }
; __device__ void phase_prep2(const Params& P, int l, unsigned char* lds) {
;     ...
;       f32x4 r = rc + (rp - rc) * *(const f32x4*)(mu + c);
;       f32x4 k = kc + (kp - kc) * *(const f32x4*)(mu + 1024 + c);
;       f32x4 v = vc + (vp - vc) * *(const f32x4*)(mu + 2048 + c);
;       if (l > 0) {
;         f32x4 vg = *(const f32x4*)(VG + o), vf = *(const f32x4*)(VF + o), vz = *(const f32x4*)(v0 + c);
; #pragma unroll
;         for (int e = 0; e < 4; ++e) v[e] = v[e] + (vf[e] - v[e]) * sigmoidf_(vz[e] + vg[e]);
;       } else { *(f32x4*)(VF + o) = v; }
;       f32x4 lw = *(const f32x4*)(LW + o), la = *(const f32x4*)(LA + o);
;       f32x4 w0v = *(const f32x4*)(w0 + c), a0v = *(const f32x4*)(a0 + c), kkv = *(const f32x4*)(k_k + c), kav = *(const f32x4*)(k_a + c);
;       f32x4 dec, al, kk, kh; float ss = 0.f;
; #pragma unroll
;       for (int e = 0; e < 4; ++e) {
;         float z = w0v[e] + lw[e];
;         float sp = fmaxf(-z, 0.f) + __logf(1.f + __expf(-fabsf(z)));
;         float wl = -sp - 0.5f;
;         dec[e] = __expf(-__expf(wl));
;         al[e] = sigmoidf_(a0v[e] + la[e]);
;         kk[e] = k[e] * kkv[e]; ss += kk[e] * kk[e];
;         kh[e] = k[e] * (1.f + (al[e] - 1.f) * kav[e]);
;       }
;       ss = sum16(ss);
;       const float inv = 1.f / fmaxf(sqrtf(ss), 1e-12f);
.LBB0_139:
	v_readlane_b32 s2, v251, 44
	v_readlane_b32 s3, v251, 45
	v_lshlrev_b32_e32 v112, 16, v16
	v_and_b32_e32 v113, 0xffff0000, v16
	v_lshl_add_u64 v[96:97], s[2:3], 0, v[90:91]
	v_readlane_b32 s2, v251, 46
	v_readlane_b32 s3, v251, 47
	v_lshlrev_b32_e32 v114, 16, v17
	v_and_b32_e32 v115, 0xffff0000, v17
	v_lshl_add_u64 v[94:95], s[2:3], 0, v[90:91]
	global_load_dwordx4 v[26:29], v[50:51], off offset:2048
	global_load_dwordx4 v[18:21], v[52:53], off offset:2048
	global_load_dwordx4 v[30:33], v[96:97], off
	global_load_dwordx4 v[22:25], v[94:95], off
	v_lshlrev_b32_e32 v116, 16, v14
	v_and_b32_e32 v117, 0xffff0000, v14
	v_lshlrev_b32_e32 v98, 16, v15
	v_and_b32_e32 v99, 0xffff0000, v15
	global_load_dwordx4 v[14:17], v[54:55], off offset:2048
	global_load_dwordx4 v[10:13], v[56:57], off offset:2048
	v_sub_f32_e32 v123, v109, v117
	v_sub_f32_e32 v122, v107, v116
	v_sub_f32_e32 v121, v106, v115
	s_waitcnt vmcnt(6)
	v_pk_fma_f32 v[106:107], v[122:123], v[2:3], v[116:117]
	v_sub_f32_e32 v119, v101, v113
	v_sub_f32_e32 v118, v41, v112
	v_sub_f32_e32 v101, v110, v99
	v_sub_f32_e32 v120, v100, v114
	v_pk_fma_f32 v[34:35], v[118:119], v[34:35], v[112:113]
	v_sub_f32_e32 v100, v108, v98
	v_pk_fma_f32 v[36:37], v[120:121], v[36:37], v[114:115]
	v_pk_fma_f32 v[4:5], v[100:101], v[4:5], v[98:99]
	s_waitcnt vmcnt(3)
	v_add_f32_e32 v0, v30, v26
	s_waitcnt vmcnt(2)
	v_add_f32_e32 v2, v22, v18
	v_add_f32_e32 v3, v23, v19
	v_mul_f32_e32 v2, 0xbfb8aa3b, v2
	v_mul_f32_e32 v3, 0xbfb8aa3b, v3
	v_exp_f32_e32 v2, v2
	v_exp_f32_e32 v3, v3
	v_add_f32_e32 v18, v31, v27
	v_max_f32_e64 v19, -v0, 0
	v_mul_f32_e64 v0, |v0|, s6
	v_mul_f32_e64 v22, |v18|, s6
	v_exp_f32_e32 v0, v0
	v_exp_f32_e32 v22, v22
	v_pk_add_f32 v[2:3], v[2:3], 1.0 op_sel_hi:[1,0]
	v_max_f32_e64 v18, -v18, 0
	v_div_scale_f32 v23, s[2:3], v3, v3, 1.0
	v_div_scale_f32 v27, s[2:3], v2, v2, 1.0
	v_add_f32_e32 v0, 1.0, v0
	s_mov_b32 s2, 0x800000
	v_add_f32_e32 v22, 1.0, v22
	v_cmp_gt_f32_e64 s[46:47], s2, v0
	v_cmp_gt_f32_e64 s[48:49], s2, v22
	v_rcp_f32_e32 v110, v23
	v_cndmask_b32_e64 v31, 0, 32, s[46:47]
	v_cndmask_b32_e64 v41, 0, 32, s[48:49]
	v_ldexp_f32 v0, v0, v31
	v_rcp_f32_e32 v111, v27
	v_ldexp_f32 v22, v22, v41
	v_log_f32_e32 v0, v0
	v_log_f32_e32 v22, v22
	v_fma_f32 v31, -v23, v110, 1.0
	v_fma_f32 v41, -v27, v111, 1.0
	v_fmac_f32_e32 v110, v31, v110
	v_mul_f32_e32 v31, 0x3f317217, v0
	s_mov_b32 s3, 0x3f317217
	v_div_scale_f32 v26, vcc, 1.0, v3, 1.0
	v_fmac_f32_e32 v111, v41, v111
	v_mul_f32_e32 v41, 0x3f317217, v22
	v_fma_f32 v31, v0, s3, -v31
	v_div_scale_f32 v30, s[44:45], 1.0, v2, 1.0
	v_mul_f32_e32 v112, v26, v110
	v_fma_f32 v41, v22, s3, -v41
	v_fmac_f32_e32 v31, 0x3377d1cf, v0
	v_cndmask_b32_e64 v108, 0, v187, s[46:47]
	v_mul_f32_e32 v113, v30, v111
	v_fma_f32 v114, -v23, v112, v26
	v_fmac_f32_e32 v41, 0x3377d1cf, v22
	v_fmac_f32_e32 v31, 0x3f317217, v0
	v_cmp_lt_f32_e64 s[46:47], |v0|, s7
	v_fma_f32 v115, -v27, v113, v30
	v_fmac_f32_e32 v112, v114, v110
	v_fmac_f32_e32 v41, 0x3f317217, v22
	v_cndmask_b32_e64 v0, v0, v31, s[46:47]
	v_cmp_lt_f32_e64 s[46:47], |v22|, s7
	v_cndmask_b32_e64 v109, 0, v187, s[48:49]
	v_fmac_f32_e32 v113, v115, v111
	v_fma_f32 v23, -v23, v112, v26
	v_cndmask_b32_e64 v22, v22, v41, s[46:47]
	v_sub_f32_e32 v0, v0, v108
	v_fma_f32 v26, -v27, v113, v30
	v_div_fmas_f32 v23, v23, v110, v112
	v_sub_f32_e32 v22, v22, v109
	s_mov_b64 vcc, s[44:45]
	v_add_f32_e32 v0, v19, v0
	v_div_fixup_f32 v27, v23, v3, 1.0
	v_div_fmas_f32 v3, v26, v111, v113
	v_add_f32_e32 v18, v18, v22
	v_sub_f32_e32 v0, -0.5, v0
	v_div_fixup_f32 v26, v3, v2, 1.0
	v_sub_f32_e32 v2, -0.5, v18
	v_mul_f32_e32 v0, 0x3fb8aa3b, v0
	v_mul_f32_e32 v2, 0x3fb8aa3b, v2
	v_exp_f32_e32 v0, v0
	v_exp_f32_e32 v2, v2
	v_add_f32_e32 v3, -1.0, v26
	s_waitcnt vmcnt(0)
	v_fma_f32 v10, v10, v3, 1.0
	v_mul_f32_e32 v0, 0xbfb8aa3b, v0
	v_mul_f32_e32 v2, 0xbfb8aa3b, v2
	v_exp_f32_e32 v18, v0
	v_add_f32_e32 v0, v32, v28
	v_exp_f32_e32 v19, v2
	v_mul_f32_e64 v2, |v0|, s6
	v_exp_f32_e32 v22, v2
	v_mul_f32_e32 v28, v106, v10
	v_max_f32_e64 v0, -v0, 0
	v_pk_mul_f32 v[2:3], v[106:107], v[14:15]
	v_add_f32_e32 v10, 1.0, v22
	v_cmp_gt_f32_e32 vcc, s2, v10
	v_pk_mul_f32 v[14:15], v[2:3], v[2:3]
	v_pk_mul_f32 v[16:17], v[4:5], v[16:17]
	v_cndmask_b32_e64 v22, 0, 32, vcc
	v_ldexp_f32 v10, v10, v22
	v_log_f32_e32 v10, v10
	v_add_f32_e32 v22, -1.0, v27
	v_fma_f32 v11, v11, v22, 1.0
	v_add_f32_e32 v14, v14, v15
	v_mul_f32_e32 v22, 0x3f317217, v10
	v_fma_f32 v22, v10, s3, -v22
	v_fmac_f32_e32 v22, 0x3377d1cf, v10
	v_fmac_f32_e32 v22, 0x3f317217, v10
	v_cmp_lt_f32_e64 s[44:45], |v10|, s7
	v_mov_b32_e32 v41, 0
	s_nop 0
	v_cndmask_b32_e64 v10, v10, v22, s[44:45]
	v_cndmask_b32_e32 v22, 0, v187, vcc
	v_sub_f32_e32 v10, v10, v22
	v_add_f32_e32 v22, v33, v29
	v_add_f32_e32 v0, v0, v10
	v_mul_f32_e64 v10, |v22|, s6
	v_exp_f32_e32 v10, v10
	v_mul_f32_e32 v29, v107, v11
	v_add_f32_e32 v11, v24, v20
	v_sub_f32_e32 v0, -0.5, v0
	v_add_f32_e32 v10, 1.0, v10
	v_cmp_gt_f32_e32 vcc, s2, v10
	v_mul_f32_e32 v0, 0x3fb8aa3b, v0
	v_exp_f32_e32 v0, v0
	v_cndmask_b32_e64 v20, 0, 32, vcc
	v_ldexp_f32 v10, v10, v20
	v_log_f32_e32 v20, v10
	v_mul_f32_e32 v10, 0xbfb8aa3b, v11
	v_max_f32_e64 v11, -v22, 0
	v_exp_f32_e32 v10, v10
	v_mul_f32_e32 v22, 0x3f317217, v20
	v_fma_f32 v22, v20, s3, -v22
	v_fmac_f32_e32 v22, 0x3377d1cf, v20
	v_fmac_f32_e32 v22, 0x3f317217, v20
	v_cmp_lt_f32_e64 s[44:45], |v20|, s7
	v_mul_f32_e32 v0, 0xbfb8aa3b, v0
	s_nop 0
	v_cndmask_b32_e64 v20, v20, v22, s[44:45]
	v_cndmask_b32_e32 v22, 0, v187, vcc
	v_sub_f32_e32 v20, v20, v22
	v_add_f32_e32 v20, v11, v20
	v_add_f32_e32 v11, v25, v21
	v_mul_f32_e32 v11, 0xbfb8aa3b, v11
	v_exp_f32_e32 v11, v11
	v_sub_f32_e32 v20, -0.5, v20
	v_mul_f32_e32 v20, 0x3fb8aa3b, v20
	v_exp_f32_e32 v21, v20
	v_pk_add_f32 v[10:11], v[10:11], 1.0 op_sel_hi:[1,0]
	v_exp_f32_e32 v20, v0
	v_div_scale_f32 v24, s[2:3], v11, v11, 1.0
	v_rcp_f32_e32 v25, v24
	v_mul_f32_e32 v0, 0xbfb8aa3b, v21
	v_exp_f32_e32 v21, v0
	v_fma_f32 v0, -v24, v25, 1.0
	v_fmac_f32_e32 v25, v0, v25
	v_div_scale_f32 v0, vcc, 1.0, v11, 1.0
	v_mul_f32_e32 v30, v0, v25
	v_fma_f32 v22, -v24, v30, v0
	v_fmac_f32_e32 v30, v22, v25
	v_pk_mul_f32 v[22:23], v[16:17], v[16:17]
	v_fma_f32 v0, -v24, v30, v0
	v_add_f32_e32 v14, v22, v14
	v_add_f32_e32 v14, v23, v14
	ds_bpermute_b32 v15, v102, v14
	v_div_scale_f32 v22, s[2:3], v10, v10, 1.0
	v_rcp_f32_e32 v23, v22
	v_div_fmas_f32 v0, v0, v25, v30
	s_waitcnt lgkmcnt(0)
; DEVI f32x4 ld_bf4(const bf16_t* p) { u32x2 u = *(const u32x2*)p; return (f32x4){bf_lo(u.x), bf_hi(u.x), bf_lo(u.y), bf_hi(u.y)}; }
; DEVI void st_bf4(bf16_t* p, f32x4 v) { u32x2 u; u.x = cvt_pk_bf16(v[0], v[1]); u.y = cvt_pk_bf16(v[2], v[3]); *(u32x2*)p = u; }
; __device__ void phase_prep2(const Params& P, int l, unsigned char* lds) {
;     ...
;     for (int i = 0; i < 4; ++i) {
;       const int c = i * 256 + lane * 4; const size_t o = (size_t)t * 1024 + c;
;       f32x4 rc = ld_bf4(pc + c), kc = ld_bf4(pc + 1024 + c), vc = ld_bf4(pc + 2048 + c);
;       f32x4 rp = hp ? ld_bf4(pp + c) : z4, kp = hp ? ld_bf4(pp + 1024 + c) : z4, vp = hp ? ld_bf4(pp + 2048 + c) : z4;
;     ...
;       ss = sum16(ss);
;       const float inv = 1.f / fmaxf(sqrtf(ss), 1e-12f);
;       kk = kk * inv;
;       *(f32x4*)(LW + o) = dec; *(f32x4*)(LA + o) = -(kk * al); *(f32x4*)(VG + o) = v; *(f32x4*)(KK + o) = kk;
;       st_bf4(KH + o, kh); st_bf4(R + o, r);
;     }
	v_add_f32_e32 v14, v14, v15
	ds_bpermute_b32 v15, v103, v14
	v_div_fixup_f32 v24, v0, v11, 1.0
	v_fma_f32 v0, -v22, v23, 1.0
	v_fmac_f32_e32 v23, v0, v23
	s_mov_b32 s2, 0xf800000
	s_waitcnt lgkmcnt(0)
	v_add_f32_e32 v0, v14, v15
	ds_bpermute_b32 v11, v104, v0
	v_div_scale_f32 v14, vcc, 1.0, v10, 1.0
	v_mul_f32_e32 v15, v14, v23
	v_fma_f32 v25, -v22, v15, v14
	s_waitcnt lgkmcnt(0)
	v_add_f32_e32 v0, v0, v11
	ds_bpermute_b32 v11, v105, v0
	v_fmac_f32_e32 v15, v25, v23
	v_fma_f32 v14, -v22, v15, v14
	v_div_fmas_f32 v14, v14, v23, v15
	v_div_fixup_f32 v14, v14, v10, 1.0
	s_waitcnt lgkmcnt(0)
	v_add_f32_e32 v0, v0, v11
	v_mul_f32_e32 v10, 0x4f800000, v0
	v_cmp_gt_f32_e32 vcc, s2, v0
	v_add_f32_e32 v11, -1.0, v14
	v_fma_f32 v11, v12, v11, 1.0
	v_cndmask_b32_e32 v0, v0, v10, vcc
	v_sqrt_f32_e32 v10, v0
	v_mul_f32_e32 v15, v4, v11
	global_store_dwordx4 v[96:97], v[18:21], off
	v_add_u32_e32 v4, -1, v10
	v_fma_f32 v11, -v4, v10, v0
	v_cmp_ge_f32_e64 s[44:45], 0, v11
	v_add_u32_e32 v11, 1, v10
	s_nop 0
	v_cndmask_b32_e64 v4, v10, v4, s[44:45]
	v_fma_f32 v10, -v11, v10, v0
	v_cmp_lt_f32_e64 s[44:45], 0, v10
	s_nop 1
	v_cndmask_b32_e64 v4, v4, v11, s[44:45]
	v_mul_f32_e32 v10, 0x37800000, v4
	v_cndmask_b32_e32 v4, v4, v10, vcc
	v_cmp_class_f32_e32 vcc, v0, v182
	v_add_f32_e32 v11, -1.0, v24
	v_fma_f32 v11, v13, v11, 1.0
	v_cndmask_b32_e32 v0, v4, v0, vcc
	v_max_f32_e32 v0, 0x2b8cbccc, v0
	v_div_scale_f32 v4, s[2:3], v0, v0, 1.0
	v_rcp_f32_e32 v10, v4
	v_mul_f32_e32 v22, v5, v11
	v_xor_b32_e32 v13, 0x80000000, v24
	v_fma_f32 v5, -v4, v10, 1.0
	v_fmac_f32_e32 v10, v5, v10
	v_div_scale_f32 v5, vcc, 1.0, v0, 1.0
	v_mul_f32_e32 v11, v5, v10
	v_fma_f32 v12, -v4, v11, v5
	v_fmac_f32_e32 v11, v12, v10
	v_fma_f32 v4, -v4, v11, v5
	v_div_fmas_f32 v4, v4, v10, v11
	v_div_fixup_f32 v0, v4, v0, 1.0
	v_pk_mul_f32 v[4:5], v[16:17], v[0:1] op_sel_hi:[1,0]
	v_pk_mul_f32 v[2:3], v[2:3], v[0:1] op_sel_hi:[1,0]
	v_xor_b32_e32 v11, 0x80000000, v27
	v_xor_b32_e32 v10, 0x80000000, v26
	v_xor_b32_e32 v12, 0x80000000, v14
	v_pk_mul_f32 v[12:13], v[4:5], v[12:13]
	v_pk_mul_f32 v[10:11], v[2:3], v[10:11]
	global_store_dwordx4 v[94:95], v[10:13], off
	global_store_dwordx4 v[92:93], v[6:9], off
	v_lshlrev_b32_e32 v0, 1, v70
	s_nop 0
	v_lshl_add_u64 v[6:7], s[30:31], 0, v[90:91]
	global_store_dwordx4 v[6:7], v[2:5], off
	v_cvt_pk_bf16_f32 v6, v28, v29
	v_cvt_pk_bf16_f32 v7, v15, v22
	v_mov_b32_e32 v8, 0
	v_mov_b32_e32 v90, 0
	v_lshlrev_b64 v[2:3], 1, v[88:89]
	v_lshl_add_u64 v[4:5], s[26:27], 0, v[2:3]
	v_lshl_add_u64 v[2:3], s[28:29], 0, v[2:3]
	global_store_dwordx2 v[4:5], v[6:7], off
	v_cvt_pk_bf16_f32 v4, v34, v35
	v_cvt_pk_bf16_f32 v5, v36, v37
	global_store_dwordx2 v[2:3], v[4:5], off
	v_lshl_add_u64 v[2:3], v[84:85], 0, v[0:1]
	global_load_dwordx2 v[16:17], v[86:87], off offset:1536
	global_load_dwordx2 v[14:15], v[86:87], off offset:3584
	global_load_dwordx2 v[6:7], v[2:3], off
	v_mov_b32_e32 v89, 0
	v_mov_b32_e32 v88, 0
	v_mov_b32_e32 v91, 0
	v_mov_b32_e32 v93, 0
	v_mov_b32_e32 v92, 0
	v_mov_b32_e32 v94, 0
	v_mov_b32_e32 v10, 0
	v_mov_b32_e32 v9, 0
	v_mov_b32_e32 v11, 0
	s_and_saveexec_b64 s[8:9], s[40:41]
	s_cbranch_execz .LBB0_145
	v_lshl_add_u64 v[124:125], v[78:79], 0, v[0:1]
	global_load_dwordx2 v[124:125], v[124:125], off
	v_lshl_add_u64 v[126:127], v[80:81], 0, v[0:1]
	global_load_dwordx2 v[126:127], v[126:127], off
	v_lshl_add_u64 v[128:129], v[82:83], 0, v[0:1]
	global_load_dwordx2 v[128:129], v[128:129], off
	s_waitcnt vmcnt(0)
	v_lshlrev_b32_e32 v41, 16, v124
	v_and_b32_e32 v89, 0xffff0000, v124
	v_lshlrev_b32_e32 v88, 16, v125
	v_and_b32_e32 v90, 0xffff0000, v125
	v_lshlrev_b32_e32 v91, 16, v126
	v_and_b32_e32 v93, 0xffff0000, v126
	v_lshlrev_b32_e32 v92, 16, v127
	v_and_b32_e32 v94, 0xffff0000, v127
	v_lshlrev_b32_e32 v8, 16, v128
	v_and_b32_e32 v10, 0xffff0000, v128
	v_lshlrev_b32_e32 v9, 16, v129
	v_and_b32_e32 v11, 0xffff0000, v129

; DEVI unsigned xb_ld(unsigned* p) { return __hip_atomic_load(p, __ATOMIC_RELAXED, __HIP_MEMORY_SCOPE_AGENT); }
; DEVI void xcd_barrier_complete(unsigned* bar, unsigned x, unsigned& nloc, unsigned& nx) {
;     ...
;   for (;;) {
;     sum = 0u; cnt = 0u; mine = 0u;
; #pragma unroll
;     for (unsigned j = 0; j < 16; ++j) { const unsigned c = xb_ld(&bar[XB_XCNT(j)]); sum += c; cnt += (c > 0u) ? 1u : 0u; mine = (j == x) ? c : mine; }
;     if (sum == G) break;
;     __builtin_amdgcn_s_sleep(1);
;     if ((++sp & 255u) == 0u) { if (xb_ld(&bar[XB_TMO])) break; if (sp > XB_SPIN_CAP) { atomicAdd(&bar[XB_TMO], 1u); break; } }
.LBB0_785:
	v_readlane_b32 s4, v252, 15
	v_readlane_b32 s5, v252, 16
	v_readlane_b32 s6, v252, 7
	s_nop 3
	global_load_dword v0, v1, s[4:5] sc1
	v_readlane_b32 s4, v252, 17
	v_readlane_b32 s5, v252, 18
	s_waitcnt lgkmcnt(0)
	s_nop 3
	global_load_dword v2, v1, s[4:5] sc1
	v_readlane_b32 s4, v252, 19
	v_readlane_b32 s5, v252, 20
	s_nop 4
	global_load_dword v3, v1, s[4:5] sc1
	v_readlane_b32 s4, v252, 21
	v_readlane_b32 s5, v252, 22
	s_nop 4
	global_load_dword v4, v1, s[4:5] sc1
	v_readlane_b32 s4, v252, 23
	v_readlane_b32 s5, v252, 24
	s_nop 4
	global_load_dword v5, v1, s[4:5] sc1
	v_readlane_b32 s4, v252, 25
	v_readlane_b32 s5, v252, 26
	s_nop 4
	global_load_dword v6, v1, s[4:5] sc1
	v_readlane_b32 s4, v252, 27
	v_readlane_b32 s5, v252, 28
	s_nop 4
	global_load_dword v7, v1, s[4:5] sc1
	v_readlane_b32 s4, v252, 29
	v_readlane_b32 s5, v252, 30
	s_nop 4
	global_load_dword v8, v1, s[4:5] sc1
	v_readlane_b32 s4, v252, 31
	v_readlane_b32 s5, v252, 32
	s_nop 4
	global_load_dword v9, v1, s[4:5] sc1
	v_readlane_b32 s4, v252, 33
	v_readlane_b32 s5, v252, 34
	s_nop 4
	global_load_dword v10, v1, s[4:5] sc1
	v_readlane_b32 s4, v252, 35
	v_readlane_b32 s5, v252, 36
	s_nop 4
	global_load_dword v11, v1, s[4:5] sc1
	v_readlane_b32 s4, v252, 37
	v_readlane_b32 s5, v252, 38
	s_nop 4
	global_load_dword v12, v1, s[4:5] sc1
	v_readlane_b32 s4, v252, 39
	v_readlane_b32 s5, v252, 40
	s_nop 4
	global_load_dword v13, v1, s[4:5] sc1
	v_readlane_b32 s4, v252, 41
	v_readlane_b32 s5, v252, 42
	s_nop 4
	global_load_dword v14, v1, s[4:5] sc1
	v_readlane_b32 s4, v252, 43
	v_readlane_b32 s5, v252, 44
	s_nop 4
	global_load_dword v15, v1, s[4:5] sc1
	v_readlane_b32 s4, v252, 45
	v_readlane_b32 s5, v252, 46
	s_nop 4
	global_load_dword v16, v1, s[4:5] sc1
	s_mov_b64 s[4:5], -1
	s_waitcnt vmcnt(0)
	v_add_u32_e32 v17, v2, v0
	v_add_u32_e32 v17, v17, v3
	v_add_u32_e32 v17, v17, v4
	v_add_u32_e32 v17, v17, v5
	v_add_u32_e32 v17, v17, v6
	v_add_u32_e32 v17, v17, v7
	v_add_u32_e32 v17, v17, v8
	v_add_u32_e32 v17, v17, v9
	v_add_u32_e32 v17, v17, v10
	v_add_u32_e32 v17, v17, v11
	v_add_u32_e32 v17, v17, v12
	v_add_u32_e32 v17, v17, v13
	v_add_u32_e32 v17, v17, v14
	v_add_u32_e32 v17, v17, v15
	v_add_u32_e32 v17, v17, v16
	v_cmp_eq_u32_e32 vcc, s6, v17
	s_mov_b64 s[6:7], -1
	s_cbranch_vccnz .LBB0_784
	s_and_b32 s4, s10, 0xff
	s_cmp_eq_u32 s4, 0
	s_mov_b64 s[4:5], -1
	s_mov_b64 s[8:9], -1
	s_sleep 1
	s_cbranch_scc1 .LBB0_789
	s_and_b64 vcc, exec, s[8:9]
	s_cbranch_vccz .LBB0_784
